# seams: the first workgroup of each XCD to arrive kicks an L2 writeback (buffer_wbl2) so the last arriver's mandatory flush finds fewer dirty lines
# speedup vs baseline: 1.0092x; 1.0072x over previous
; __device__ __forceinline__ unsigned xb_ld(unsigned* p)              { return __hip_atomic_load(p, __ATOMIC_RELAXED, __HIP_MEMORY_SCOPE_AGENT); }
; __device__ __forceinline__ unsigned xb_add(unsigned* p, unsigned v) { return __hip_atomic_fetch_add(p, v, __ATOMIC_RELAXED, __HIP_MEMORY_SCOPE_AGENT); }
; #define XB_SPIN(cond, bar) do { unsigned _sp = 0; while (cond) { __builtin_amdgcn_s_sleep(1); \
;     if ((++_sp & 255u) == 0u) { if (xb_ld(&(bar)[XB_TMO])) break; if (_sp > XB_SPIN_CAP) { atomicAdd(&(bar)[XB_TMO], 1u); break; } } } } while (0)
; __device__ __forceinline__ void xcd_barrier(const XcdBarrier& b) {
;     ...
;         const unsigned old = xb_add(&bar[XB_XSUB(b.x)], 1u);
;         const unsigned gen = old / nloc;
;         if (old + 1u == (gen + 1u) * nloc) {
;             __builtin_amdgcn_fence(__ATOMIC_RELEASE, "agent");
;             asm volatile("s_waitcnt vmcnt(0)" ::: "memory");
;             const unsigned og = xb_add(&bar[XB_TOP], 1u);
;             const unsigned tg = og / nx;
;             if (og + 1u == (tg + 1u) * nx) xb_add(&bar[XB_TOPGEN], 1u);
;             else XB_SPIN(xb_ld(&bar[XB_TOPGEN]) == tg, bar);
;             __builtin_amdgcn_fence(__ATOMIC_ACQUIRE, "agent");
;             xb_add(&bar[XB_XGEN(b.x)], 1u);
;             asm volatile("s_waitcnt vmcnt(0)" ::: "memory");
;         } else {
;             XB_SPIN(xb_ld(&bar[XB_XGEN(b.x)]) == gen, bar);
;             __builtin_amdgcn_fence(__ATOMIC_ACQUIRE, "agent");
;             asm volatile("s_waitcnt vmcnt(0)" ::: "memory");
;         }
.LBB0_380:
	s_or_b64 exec, exec, s[8:9]
	v_cvt_f32_u32_e32 v4, v2
	s_waitcnt vmcnt(0)
	v_readfirstlane_b32 s6, v3
	v_sub_u32_e32 v3, 0, v2
	v_rcp_iflag_f32_e32 v4, v4
	v_add_u32_e32 v5, s6, v1
	v_mul_f32_e32 v4, 0x4f7ffffe, v4
	v_cvt_u32_f32_e32 v4, v4
	v_mul_lo_u32 v1, v3, v4
	v_mul_hi_u32 v1, v4, v1
	v_add_u32_e32 v1, v4, v1
	v_mul_hi_u32 v1, v5, v1
	v_mul_lo_u32 v3, v1, v2
	v_sub_u32_e32 v3, v5, v3
	v_add_u32_e32 v4, 1, v1
	v_cmp_ge_u32_e32 vcc, v3, v2
	s_nop 1
	v_cndmask_b32_e32 v1, v1, v4, vcc
	v_sub_u32_e32 v4, v3, v2
	v_cndmask_b32_e32 v3, v3, v4, vcc
	v_add_u32_e32 v4, 1, v1
	v_cmp_ge_u32_e32 vcc, v3, v2
	v_add_u32_e32 v3, 1, v5
	s_nop 0
	v_cndmask_b32_e32 v1, v1, v4, vcc
	v_mul_lo_u32 v4, v2, v1
	v_cmp_eq_u32_e32 vcc, v5, v4
	s_and_saveexec_b64 s[6:7], vcc
	s_cbranch_execz .Lwb_skip_1
	buffer_wbl2 sc1
.Lwb_skip_1:
	s_or_b64 exec, exec, s[6:7]
	s_nop 0
	s_nop 0
	s_nop 0
	s_nop 0
	s_nop 0
	s_nop 0
	s_nop 0
	s_nop 0
	s_nop 0
	s_nop 0
	v_add_u32_e32 v2, v4, v2
	v_cmp_ne_u32_e32 vcc, v3, v2
	s_and_saveexec_b64 s[6:7], vcc
	s_xor_b64 s[6:7], exec, s[6:7]
	s_cbranch_execz .LBB0_394
	s_waitcnt lgkmcnt(0)
	v_mov_b32_e32 v0, 0x2000
	global_load_dword v0, v0, s[4:5] offset:1024 sc1
	s_add_u32 s14, s4, 0x2400
	s_addc_u32 s15, s5, 0
	s_waitcnt vmcnt(0)
	v_cmp_eq_u32_e32 vcc, v0, v1
	s_and_saveexec_b64 s[8:9], vcc
	s_cbranch_execz .LBB0_393
	s_add_u32 s12, s82, 0x80200
	s_addc_u32 s13, s83, 0
	s_mov_b32 s26, 1
	s_mov_b64 s[16:17], 0
	v_mov_b32_e32 v0, 0
	s_branch .LBB0_384

; __device__ __forceinline__ unsigned xb_ld(unsigned* p)              { return __hip_atomic_load(p, __ATOMIC_RELAXED, __HIP_MEMORY_SCOPE_AGENT); }
; __device__ __forceinline__ unsigned xb_add(unsigned* p, unsigned v) { return __hip_atomic_fetch_add(p, v, __ATOMIC_RELAXED, __HIP_MEMORY_SCOPE_AGENT); }
; #define XB_SPIN(cond, bar) do { unsigned _sp = 0; while (cond) { __builtin_amdgcn_s_sleep(1); \
;     if ((++_sp & 255u) == 0u) { if (xb_ld(&(bar)[XB_TMO])) break; if (_sp > XB_SPIN_CAP) { atomicAdd(&(bar)[XB_TMO], 1u); break; } } } } while (0)
; __device__ __forceinline__ void xcd_barrier(const XcdBarrier& b) {
;     ...
;         const unsigned old = xb_add(&bar[XB_XSUB(b.x)], 1u);
;         const unsigned gen = old / nloc;
;         if (old + 1u == (gen + 1u) * nloc) {
;             __builtin_amdgcn_fence(__ATOMIC_RELEASE, "agent");
;             asm volatile("s_waitcnt vmcnt(0)" ::: "memory");
;             const unsigned og = xb_add(&bar[XB_TOP], 1u);
;             const unsigned tg = og / nx;
;             if (og + 1u == (tg + 1u) * nx) xb_add(&bar[XB_TOPGEN], 1u);
;             else XB_SPIN(xb_ld(&bar[XB_TOPGEN]) == tg, bar);
;             __builtin_amdgcn_fence(__ATOMIC_ACQUIRE, "agent");
;             xb_add(&bar[XB_XGEN(b.x)], 1u);
;             asm volatile("s_waitcnt vmcnt(0)" ::: "memory");
;         } else {
;             XB_SPIN(xb_ld(&bar[XB_XGEN(b.x)]) == gen, bar);
;             __builtin_amdgcn_fence(__ATOMIC_ACQUIRE, "agent");
;             asm volatile("s_waitcnt vmcnt(0)" ::: "memory");
;         }
.Lwb_skip_2:
	s_or_b64 exec, exec, s[6:7]
	s_nop 0
	s_nop 0
	s_nop 0
	s_nop 0
	s_nop 0
	s_nop 0
	s_nop 0
	s_nop 0
	s_nop 0
	s_nop 0
	v_add_u32_e32 v2, v4, v2
	v_cmp_ne_u32_e32 vcc, v3, v2
	s_and_saveexec_b64 s[6:7], vcc
	s_xor_b64 s[6:7], exec, s[6:7]
	s_cbranch_execz .LBB0_659
	s_waitcnt lgkmcnt(0)
	v_mov_b32_e32 v0, 0x2000
	global_load_dword v0, v0, s[4:5] offset:1024 sc1
	s_add_u32 s12, s4, 0x2400
	s_addc_u32 s13, s5, 0
	s_waitcnt vmcnt(0)
	v_cmp_eq_u32_e32 vcc, v0, v1
	s_and_saveexec_b64 s[8:9], vcc
	s_cbranch_execz .LBB0_658
	s_add_u32 s10, s82, 0x80200
	s_addc_u32 s11, s83, 0
	s_mov_b32 s24, 1
	s_mov_b64 s[14:15], 0
	v_mov_b32_e32 v0, 0
	s_branch .LBB0_649

; __device__ __forceinline__ unsigned xb_ld(unsigned* p)              { return __hip_atomic_load(p, __ATOMIC_RELAXED, __HIP_MEMORY_SCOPE_AGENT); }
; __device__ __forceinline__ unsigned xb_add(unsigned* p, unsigned v) { return __hip_atomic_fetch_add(p, v, __ATOMIC_RELAXED, __HIP_MEMORY_SCOPE_AGENT); }
; #define XB_SPIN(cond, bar) do { unsigned _sp = 0; while (cond) { __builtin_amdgcn_s_sleep(1); \
;     if ((++_sp & 255u) == 0u) { if (xb_ld(&(bar)[XB_TMO])) break; if (_sp > XB_SPIN_CAP) { atomicAdd(&(bar)[XB_TMO], 1u); break; } } } } while (0)
; __device__ __forceinline__ void xcd_barrier(const XcdBarrier& b) {
;     ...
;         const unsigned old = xb_add(&bar[XB_XSUB(b.x)], 1u);
;         const unsigned gen = old / nloc;
;         if (old + 1u == (gen + 1u) * nloc) {
;             __builtin_amdgcn_fence(__ATOMIC_RELEASE, "agent");
;             asm volatile("s_waitcnt vmcnt(0)" ::: "memory");
;             const unsigned og = xb_add(&bar[XB_TOP], 1u);
;             const unsigned tg = og / nx;
;             if (og + 1u == (tg + 1u) * nx) xb_add(&bar[XB_TOPGEN], 1u);
;             else XB_SPIN(xb_ld(&bar[XB_TOPGEN]) == tg, bar);
;             __builtin_amdgcn_fence(__ATOMIC_ACQUIRE, "agent");
;             xb_add(&bar[XB_XGEN(b.x)], 1u);
;             asm volatile("s_waitcnt vmcnt(0)" ::: "memory");
;         } else {
;             XB_SPIN(xb_ld(&bar[XB_XGEN(b.x)]) == gen, bar);
;             __builtin_amdgcn_fence(__ATOMIC_ACQUIRE, "agent");
;             asm volatile("s_waitcnt vmcnt(0)" ::: "memory");
;         }
.Lwb_skip_9:
	s_or_b64 exec, exec, s[6:7]
	s_nop 0
	s_nop 0
	s_nop 0
	s_nop 0
	s_nop 0
	s_nop 0
	s_nop 0
	s_nop 0
	s_nop 0
	s_nop 0
	v_add_u32_e32 v2, v4, v2
	v_cmp_ne_u32_e32 vcc, v3, v2
	s_and_saveexec_b64 s[6:7], vcc
	s_xor_b64 s[6:7], exec, s[6:7]
	s_cbranch_execz .LBB0_1635
	s_waitcnt lgkmcnt(0)
	v_mov_b32_e32 v0, 0x2000
	global_load_dword v0, v0, s[4:5] offset:1024 sc1
	s_add_u32 s14, s4, 0x2400
	s_addc_u32 s15, s5, 0
	s_waitcnt vmcnt(0)
	v_cmp_eq_u32_e32 vcc, v0, v1
	s_and_saveexec_b64 s[8:9], vcc
	s_cbranch_execz .LBB0_1634
	s_add_u32 s10, s82, 0x80200
	s_addc_u32 s11, s83, 0
	s_mov_b32 s26, 1
	s_mov_b64 s[16:17], 0
	v_mov_b32_e32 v0, 0
	s_branch .LBB0_1625
